# retention scan: zero-padded K=32 bf16 MFMAs (intra-chunk PV and state update) issued as 16x16x16 bf16 on the live register pairs; padding/copy v_movs removed
# speedup vs baseline: 1.0061x; 1.0034x over previous
; __device__ __forceinline__ unsigned pk2(float lo, float hi) { f32x2_t v = {lo, hi}; bf16x2_t b = __builtin_convertvector(v, bf16x2_t); return __builtin_bit_cast(unsigned, b); }
; __device__ __forceinline__ bf16_t f2bf(float f) { return (bf16_t)(pk2(f, 0.f) & 0xffffu); }
; template <int MODE>
; __device__ void scan_unit(int swave, const Params& p, int j, int b, int h, int dir, char* shm) {
;     ...
; #pragma unroll
;     for (int m = 0; m < 2; ++m)
; #pragma unroll
;       for (int t = 0; t < NVT; ++t) {
;         const f32x4 s0 = S[2 * m][t], s1 = S[2 * m + 1][t];
;         union { unsigned u[4]; bf16x8 v; } cv;
;         cv.u[0] = pk2(s0[0], s0[1]); cv.u[1] = pk2(s0[2], s0[3]); cv.u[2] = pk2(s1[0], s1[1]); cv.u[3] = pk2(s1[2], s1[3]);
;         o[t] = __builtin_amdgcn_mfma_f32_16x16x32_bf16(Aq[m], cv.v, o[t], 0, 0, 0);
;       }
; #pragma unroll
;     for (int t = 0; t < NVT; ++t)
; #pragma unroll
;       for (int jj = 0; jj < 4; ++jj) obuf[(wk * 16 + q4 * 4 + jj) * OS + (vt0 + t) * 16 + r] = f2bf(o[t][jj]);
; #pragma unroll
;     for (int kt = 0; kt < 4; ++kt) {
;       const uint2 kk = *(const uint2*)(koutT + (slab + kt * 16 + r) * 16 + q4 * 4);
;       const bf16x8 Ak = {(short)(kk.x & 0xffff), (short)(kk.x >> 16), (short)(kk.y & 0xffff), (short)(kk.y >> 16), 0, 0, 0, 0};
;       const f32x4 dc = *(const f32x4*)(dec + slab + kt * 16 + q4 * 4);
; #pragma unroll
;       for (int t = 0; t < NVT; ++t) S[kt][t] = __builtin_amdgcn_mfma_f32_16x16x32_bf16(Ak, Bv[t], S[kt][t] * dc, 0, 0, 0);
;     }
.LBB0_570:
	s_or_b64 exec, exec, s[2:3]
	s_waitcnt lgkmcnt(1)
	v_bfi_b32 v30, s30, v30, v30
	s_waitcnt lgkmcnt(0)
	v_bfi_b32 v26, s30, v26, v26
	v_cvt_pk_bf16_f32 v52, v96, v97
	v_cvt_pk_bf16_f32 v53, v98, v99
	v_cvt_pk_bf16_f32 v54, v20, v21
	v_cvt_pk_bf16_f32 v55, v22, v23
	s_add_i32 s24, s24, 2
	s_and_b64 vcc, exec, s[50:51]
	v_mfma_f32_16x16x32_bf16 v[44:47], v[28:31], v[52:55], v[44:47]
	v_cvt_pk_bf16_f32 v52, v92, v93
	v_cvt_pk_bf16_f32 v53, v94, v95
	v_cvt_pk_bf16_f32 v54, v12, v13
	v_cvt_pk_bf16_f32 v55, v14, v15
	s_nop 1
	v_mfma_f32_16x16x32_bf16 v[40:43], v[28:31], v[52:55], v[40:43]
	v_cvt_pk_bf16_f32 v52, v88, v89
	v_cvt_pk_bf16_f32 v53, v90, v91
	v_cvt_pk_bf16_f32 v54, v16, v17
	v_cvt_pk_bf16_f32 v55, v18, v19
	s_nop 1
	v_mfma_f32_16x16x32_bf16 v[28:31], v[28:31], v[52:55], v[48:51]
	s_nop 2
	v_cvt_pk_bf16_f32 v48, v68, v69
	v_cvt_pk_bf16_f32 v49, v70, v71
	v_cvt_pk_bf16_f32 v50, v80, v81
	v_cvt_pk_bf16_f32 v51, v82, v83
	s_nop 1
	v_mfma_f32_16x16x32_bf16 v[44:47], v[24:27], v[48:51], v[44:47]
	v_cvt_pk_bf16_f32 v48, v32, v33
	v_cvt_pk_bf16_f32 v49, v34, v35
	v_cvt_pk_bf16_f32 v50, v76, v77
	v_cvt_pk_bf16_f32 v51, v78, v79
	s_nop 1
	v_mfma_f32_16x16x32_bf16 v[40:43], v[24:27], v[48:51], v[40:43]
	v_cvt_pk_bf16_f32 v48, v36, v37
	v_cvt_pk_bf16_f32 v49, v38, v39
	v_cvt_pk_bf16_f32 v50, v72, v73
	v_cvt_pk_bf16_f32 v51, v74, v75
	s_nop 1
	v_mfma_f32_16x16x32_bf16 v[24:27], v[24:27], v[48:51], v[28:31]
	s_nop 0
	s_nop 1
	v_cvt_pk_bf16_f32 v28, v44, s0
	ds_write_b16 v207, v28
	v_cvt_pk_bf16_f32 v28, v45, s0
	ds_write_b16 v208, v28
	v_cvt_pk_bf16_f32 v28, v46, s0
	ds_write_b16 v209, v28
	v_cvt_pk_bf16_f32 v28, v47, s0
	ds_write_b16 v210, v28
	v_cvt_pk_bf16_f32 v28, v40, s0
	ds_write_b16 v211, v28
	v_cvt_pk_bf16_f32 v28, v41, s0
	ds_write_b16 v212, v28
	v_cvt_pk_bf16_f32 v28, v42, s0
	ds_write_b16 v213, v28
	v_cvt_pk_bf16_f32 v28, v43, s0
	v_cvt_pk_bf16_f32 v24, v24, s0
	ds_write_b16 v214, v28
	ds_write_b16 v215, v24
	v_cvt_pk_bf16_f32 v24, v25, s0
	ds_write_b16 v216, v24
	v_cvt_pk_bf16_f32 v24, v26, s0
	ds_write_b16 v217, v24
	v_cvt_pk_bf16_f32 v24, v27, s0
	ds_write_b16 v218, v24
	ds_read_b64 v[40:41], v219
	ds_read_b128 v[44:47], v220
	ds_read_b64 v[48:49], v221
	ds_read_b128 v[52:55], v220 offset:64
	ds_read_b128 v[84:87], v220 offset:192
	s_waitcnt lgkmcnt(3)
	v_pk_mul_f32 v[26:27], v[98:99], v[46:47]
	s_waitcnt lgkmcnt(1)
	v_pk_mul_f32 v[14:15], v[14:15], v[54:55]
	v_pk_mul_f32 v[12:13], v[12:13], v[52:53]
	v_pk_mul_f32 v[24:25], v[96:97], v[44:45]
	v_pk_mul_f32 v[30:31], v[94:95], v[46:47]
	v_mfma_f32_16x16x16_bf16 v[60:63], v[48:49], v[104:105], v[12:15]
	v_mul_f32_e64 v28, v92, v44
	v_mul_f32_e64 v29, v93, v45
	v_pk_mul_f32 v[46:47], v[90:91], v[46:47]
	v_pk_mul_f32 v[44:45], v[88:89], v[44:45]
	ds_read_b64 v[12:13], v222
	v_pk_mul_f32 v[22:23], v[22:23], v[54:55]
	v_pk_mul_f32 v[20:21], v[20:21], v[52:53]
	v_mfma_f32_16x16x16_bf16 v[24:27], v[40:41], v[0:1], v[24:27]
	v_pk_mul_f32 v[18:19], v[18:19], v[54:55]
	v_mfma_f32_16x16x16_bf16 v[28:31], v[40:41], v[104:105], v[28:31]
	v_mul_f32_e64 v16, v16, v52
	v_mul_f32_e64 v17, v17, v53
	v_mfma_f32_16x16x16_bf16 v[40:43], v[40:41], v[100:101], v[44:47]
	s_nop 2
	ds_read_b128 v[44:47], v220 offset:128
	v_mfma_f32_16x16x16_bf16 v[64:67], v[48:49], v[0:1], v[20:23]
	s_nop 2
	ds_read_b64 v[20:21], v223
	v_mfma_f32_16x16x16_bf16 v[56:59], v[48:49], v[100:101], v[16:19]
	s_waitcnt lgkmcnt(0)
	s_barrier
	s_waitcnt lgkmcnt(1)
	s_nop 0
	v_pk_mul_f32 v[18:19], v[70:71], v[46:47]
	v_pk_mul_f32 v[16:17], v[68:69], v[44:45]
	s_waitcnt vmcnt(6)
	v_mov_b32_e32 v68, v113
	v_mov_b32_e32 v69, v114
	v_mfma_f32_16x16x16_bf16 v[52:55], v[12:13], v[0:1], v[16:19]
	s_waitcnt vmcnt(1)
	v_mov_b32_e32 v70, v4
	v_mov_b32_e32 v71, v6
	v_mov_b32_e32 v6, v5
	v_pk_mul_f32 v[18:19], v[34:35], v[46:47]
	v_pk_mul_f32 v[16:17], v[32:33], v[44:45]
	s_nop 1
	v_mfma_f32_16x16x16_bf16 v[48:51], v[12:13], v[104:105], v[16:19]
	s_nop 2
	v_mul_f32_e64 v18, v38, v46
	v_mul_f32_e64 v19, v39, v47
	v_pk_mul_f32 v[16:17], v[36:37], v[44:45]
	s_nop 1
	v_mfma_f32_16x16x16_bf16 v[44:47], v[12:13], v[100:101], v[16:19]
	v_mul_f32_e64 v14, v82, v86
	v_mul_f32_e64 v15, v83, v87
	v_pk_mul_f32 v[12:13], v[80:81], v[84:85]
	s_waitcnt lgkmcnt(0)
	s_nop 0
	v_mfma_f32_16x16x16_bf16 v[36:39], v[20:21], v[0:1], v[12:15]
	s_waitcnt vmcnt(0)
	v_mov_b32_e32 v0, v109
	v_mov_b32_e32 v1, v110
	v_pk_mul_f32 v[14:15], v[78:79], v[86:87]
	v_pk_mul_f32 v[12:13], v[76:77], v[84:85]
	s_nop 1
	v_mfma_f32_16x16x16_bf16 v[32:35], v[20:21], v[104:105], v[12:15]
	s_nop 2
	v_mul_f32_e64 v14, v74, v86
	v_mul_f32_e64 v15, v75, v87
	v_pk_mul_f32 v[12:13], v[72:73], v[84:85]
	s_nop 1
	v_mfma_f32_16x16x16_bf16 v[20:23], v[20:21], v[100:101], v[12:15]
	s_cbranch_vccnz .LBB0_621

; template <int MODE>
; __device__ void scan_unit(int swave, const Params& p, int j, int b, int h, int dir, char* shm) {
;     ...
;     bf16x8 Asc = {0, 0, 0, 0, 0, 0, 0, 0};
;     if (KS == 1 || wk == 0) {
;       f32x4 sc = {0.f, 0.f, 0.f, 0.f};
; #pragma unroll
;       for (int m = 0; m < DK / 32; ++m) {
;         const bf16x8 a = *(const bf16x8*)(ktil + r * QS + m * 32 + q4 * 8);
;         const bf16x8 bb = *(const bf16x8*)(qin + r * QS + m * 32 + q4 * 8);
;         sc = __builtin_amdgcn_mfma_f32_16x16x32_bf16(a, bb, sc, 0, 0, 0);
;       }
;       {
;         const unsigned p01 = pk2(q4 * 4 + 0 > r ? 0.f : sc[0], q4 * 4 + 1 > r ? 0.f : sc[1]);
;         const unsigned p23 = pk2(q4 * 4 + 2 > r ? 0.f : sc[2], q4 * 4 + 3 > r ? 0.f : sc[3]);
;         Asc[0] = (short)(p01 & 0xffff); Asc[1] = (short)(p01 >> 16); Asc[2] = (short)(p23 & 0xffff); Asc[3] = (short)(p23 >> 16);
;       }
;     }
;     bf16x8 Bv[NVT];
; #pragma unroll
;     for (int t = 0; t < NVT; ++t) {
;       const uint2 vv = *(const uint2*)(vT + ((vt0 + t) * 16 + r) * VS + q4 * 4);
;       Bv[t] = (bf16x8){(short)(vv.x & 0xffff), (short)(vv.x >> 16), (short)(vv.y & 0xffff), (short)(vv.y >> 16), 0, 0, 0, 0};
;     }
;     bf16x8 Aq[2];
; #pragma unroll
;     for (int m = 0; m < 2; ++m) {
;       const uint2 lo = *(const uint2*)(qin + r * QS + slab + (2 * m) * 16 + q4 * 4);
;       const uint2 hi = *(const uint2*)(qin + r * QS + slab + (2 * m + 1) * 16 + q4 * 4);
;       Aq[m] = (bf16x8){(short)(lo.x & 0xffff), (short)(lo.x >> 16), (short)(lo.y & 0xffff), (short)(lo.y >> 16),
;                        (short)(hi.x & 0xffff), (short)(hi.x >> 16), (short)(hi.y & 0xffff), (short)(hi.y >> 16)};
;     }
;     f32x4 o[NVT];
; #pragma unroll
;     for (int t = 0; t < NVT; ++t) {
;       o[t] = (f32x4){0.f, 0.f, 0.f, 0.f};
;       if (KS == 1 || wk == 0) o[t] = __builtin_amdgcn_mfma_f32_16x16x32_bf16(Asc, Bv[t], o[t], 0, 0, 0);
;     }
; #pragma unroll
;     for (int m = 0; m < 2; ++m)
; #pragma unroll
;       for (int t = 0; t < NVT; ++t) {
;         const f32x4 s0 = S[2 * m][t], s1 = S[2 * m + 1][t];
;         union { unsigned u[4]; bf16x8 v; } cv;
;         cv.u[0] = pk2(s0[0], s0[1]); cv.u[1] = pk2(s0[2], s0[3]); cv.u[2] = pk2(s1[0], s1[1]); cv.u[3] = pk2(s1[2], s1[3]);
;         o[t] = __builtin_amdgcn_mfma_f32_16x16x32_bf16(Aq[m], cv.v, o[t], 0, 0, 0);
;       }
; #pragma unroll
.LBB0_580:
	s_or_b64 exec, exec, s[2:3]
	v_mov_b32_e32 v4, 0
	v_mov_b32_e32 v68, 0
	v_mov_b32_e32 v69, 0
	ds_write_b16 v159, v108
	ds_write_b16_d16_hi v230, v108
	ds_write_b16 v231, v0
	ds_write_b16_d16_hi v232, v0
	ds_write_b16 v233, v1
	ds_write_b16_d16_hi v234, v1
	s_and_saveexec_b64 s[2:3], s[6:7]
	s_cbranch_execz .LBB0_582
	ds_read_b128 v[6:9], v160 offset:4352
	ds_read_b128 v[68:71], v160
	ds_read_b128 v[76:79], v160 offset:4416
	ds_read_b128 v[80:83], v160 offset:64
	ds_read_b128 v[72:75], v160 offset:4480
	s_pack_ll_b32_b16 s20, 0, 0
	s_waitcnt lgkmcnt(3)
	v_mfma_f32_16x16x32_bf16 v[6:9], v[6:9], v[68:71], 0
	ds_read_b128 v[68:71], v160 offset:128
	s_waitcnt lgkmcnt(2)
	v_mfma_f32_16x16x32_bf16 v[6:9], v[76:79], v[80:83], v[6:9]
	ds_read_b128 v[76:79], v160 offset:4544
	ds_read_b128 v[80:83], v160 offset:192
	s_waitcnt lgkmcnt(2)
	v_mfma_f32_16x16x32_bf16 v[6:9], v[72:75], v[68:71], v[6:9]
	s_waitcnt lgkmcnt(0)
	v_mfma_f32_16x16x32_bf16 v[6:9], v[76:79], v[80:83], v[6:9]
	s_nop 5
	s_nop 1
	v_cndmask_b32_e64 v0, v6, 0, s[8:9]
	v_cndmask_b32_e64 v1, 0, v7, s[10:11]
	v_cvt_pk_bf16_f32 v68, v0, v1
	v_cndmask_b32_e64 v0, v8, 0, s[12:13]
	v_cndmask_b32_e64 v1, v9, 0, s[14:15]
	v_cvt_pk_bf16_f32 v69, v0, v1
.LBB0_582:
	s_or_b64 exec, exec, s[2:3]
	ds_read_b64 v[0:1], v175 offset:12800
	ds_read_b64 v[72:73], v176 offset:12800
	ds_read_b64 v[76:77], v177 offset:12800
	ds_read2_b64 v[82:85], v224 offset1:4
	ds_read2_b64 v[8:11], v224 offset0:8 offset1:12
	v_mov_b32_e32 v86, 0
	v_mov_b32_e32 v87, 0
	v_mov_b32_e32 v88, 0
	v_mov_b32_e32 v89, 0
	s_and_saveexec_b64 s[2:3], s[6:7]
	s_cbranch_execz .LBB0_584
	s_waitcnt lgkmcnt(4)
	v_mfma_f32_16x16x16_bf16 v[86:89], v[68:69], v[0:1], 0
.LBB0_584:
	s_or_b64 exec, exec, s[2:3]
	v_mov_b32_e32 v5, 0
	v_mov_b32_e32 v6, 0
	v_mov_b32_e32 v7, 0
	s_and_saveexec_b64 s[2:3], s[6:7]
	s_cbranch_execz .LBB0_586
	s_waitcnt lgkmcnt(3)
	v_mfma_f32_16x16x16_bf16 v[4:7], v[68:69], v[72:73], 0
.LBB0_586:
	s_or_b64 exec, exec, s[2:3]
	v_mov_b32_e32 v80, 0
	v_mov_b32_e32 v90, 0
	v_mov_b32_e32 v91, 0
	v_mov_b32_e32 v92, 0
	v_mov_b32_e32 v93, 0
	s_and_saveexec_b64 s[2:3], s[6:7]
	s_cbranch_execz .LBB0_588
	s_waitcnt lgkmcnt(2)
	v_mfma_f32_16x16x16_bf16 v[90:93], v[68:69], v[76:77], 0
.LBB0_588:
	s_or_b64 exec, exec, s[2:3]
	s_waitcnt lgkmcnt(1)
	v_bfi_b32 v84, s30, v84, v84
	s_waitcnt lgkmcnt(0)
	v_bfi_b32 v10, s30, v10, v10
	v_cvt_pk_bf16_f32 v68, v24, v25
	v_cvt_pk_bf16_f32 v69, v26, v27
	v_cvt_pk_bf16_f32 v70, v64, v65
	v_cvt_pk_bf16_f32 v71, v66, v67
	v_mov_b32_e32 v81, 0
	s_nop 0
	v_mfma_f32_16x16x32_bf16 v[68:71], v[82:85], v[68:71], v[86:89]
	s_nop 2
	v_cvt_pk_bf16_f32 v86, v28, v29
	v_cvt_pk_bf16_f32 v87, v30, v31
	v_cvt_pk_bf16_f32 v88, v60, v61
	v_cvt_pk_bf16_f32 v89, v62, v63
	s_nop 1
	v_mfma_f32_16x16x32_bf16 v[4:7], v[82:85], v[86:89], v[4:7]
	v_cvt_pk_bf16_f32 v86, v40, v41
	v_cvt_pk_bf16_f32 v87, v42, v43
	v_cvt_pk_bf16_f32 v88, v56, v57
	v_cvt_pk_bf16_f32 v89, v58, v59
	s_nop 1
	v_mfma_f32_16x16x32_bf16 v[82:85], v[82:85], v[86:89], v[90:93]
	v_cvt_pk_bf16_f32 v86, v52, v53
	v_cvt_pk_bf16_f32 v87, v54, v55
	v_cvt_pk_bf16_f32 v88, v36, v37
	v_cvt_pk_bf16_f32 v89, v38, v39
	s_nop 1
	v_mfma_f32_16x16x32_bf16 v[68:71], v[8:11], v[86:89], v[68:71]
	v_cvt_pk_bf16_f32 v86, v48, v49
	v_cvt_pk_bf16_f32 v87, v50, v51
	v_cvt_pk_bf16_f32 v88, v32, v33
	v_cvt_pk_bf16_f32 v89, v34, v35
	s_nop 1
	v_mfma_f32_16x16x32_bf16 v[4:7], v[8:11], v[86:89], v[4:7]
	s_nop 0
	v_cvt_pk_bf16_f32 v68, v68, s0
	ds_write_b16 v161, v68
	v_cvt_pk_bf16_f32 v68, v69, s0
	v_cvt_pk_bf16_f32 v86, v44, v45
	v_cvt_pk_bf16_f32 v87, v46, v47
	v_cvt_pk_bf16_f32 v88, v20, v21
	v_cvt_pk_bf16_f32 v89, v22, v23
	ds_write_b16 v162, v68
	v_cvt_pk_bf16_f32 v68, v70, s0
	v_mfma_f32_16x16x32_bf16 v[8:11], v[8:11], v[86:89], v[82:85]
	ds_write_b16 v163, v68
	v_cvt_pk_bf16_f32 v68, v71, s0
	v_cvt_pk_bf16_f32 v4, v4, s0
	ds_write_b16 v164, v68
	ds_write_b16 v165, v4
	v_cvt_pk_bf16_f32 v4, v5, s0
	ds_write_b16 v166, v4
	v_cvt_pk_bf16_f32 v4, v6, s0
	ds_write_b16 v167, v4
	v_cvt_pk_bf16_f32 v4, v7, s0
	ds_write_b16 v168, v4
	v_cvt_pk_bf16_f32 v4, v8, s0
	ds_write_b16 v169, v4
	v_cvt_pk_bf16_f32 v4, v9, s0
	ds_write_b16 v170, v4
	v_cvt_pk_bf16_f32 v4, v10, s0
	ds_write_b16 v171, v4
	v_cvt_pk_bf16_f32 v4, v11, s0
	ds_write_b16 v172, v4
	ds_read2st64_b64 v[68:71], v173 offset0:17 offset1:18
	ds_read2st64_b64 v[82:85], v173 offset0:19 offset1:20
	ds_read_b128 v[90:93], v174 offset:20480
	ds_read_b128 v[236:239], v174 offset:20544
	s_waitcnt lgkmcnt(3)
	v_mov_b32_e32 v86, v68
	v_mov_b32_e32 v87, v69
	s_waitcnt lgkmcnt(1)
	v_pk_mul_f32 v[6:7], v[26:27], v[92:93]
	v_pk_mul_f32 v[4:5], v[24:25], v[90:91]
	v_pk_mul_f32 v[10:11], v[30:31], v[92:93]
	v_pk_mul_f32 v[8:9], v[28:29], v[90:91]
	v_pk_mul_f32 v[26:27], v[42:43], v[92:93]
	v_pk_mul_f32 v[24:25], v[40:41], v[90:91]
	v_mfma_f32_16x16x16_bf16 v[4:7], v[68:69], v[0:1], v[4:7]
	v_mov_b32_e32 v68, v82
	v_mov_b32_e32 v69, v83
	s_waitcnt lgkmcnt(0)
	v_pk_mul_f32 v[42:43], v[66:67], v[238:239]
	v_mfma_f32_16x16x16_bf16 v[8:11], v[86:87], v[72:73], v[8:11]
	v_mul_f32_e64 v40, v64, v236
	v_mul_f32_e64 v41, v65, v237
	v_pk_mul_f32 v[62:63], v[62:63], v[238:239]
	v_pk_mul_f32 v[60:61], v[60:61], v[236:237]
	v_mfma_f32_16x16x16_bf16 v[28:31], v[86:87], v[76:77], v[24:27]
	ds_read_b128 v[86:89], v174 offset:20608
	v_pk_mul_f32 v[58:59], v[58:59], v[238:239]
	v_pk_mul_f32 v[56:57], v[56:57], v[236:237]
	v_mov_b32_e32 v24, v70
	v_mov_b32_e32 v25, v71
	s_nop 1
	v_mfma_f32_16x16x16_bf16 v[40:43], v[24:25], v[0:1], v[40:43]
	v_mfma_f32_16x16x16_bf16 v[60:63], v[24:25], v[72:73], v[60:63]
	v_mfma_f32_16x16x16_bf16 v[64:67], v[24:25], v[76:77], v[56:59]
	ds_read_b128 v[24:27], v174 offset:20672
	s_waitcnt lgkmcnt(1)
	v_pk_mul_f32 v[46:47], v[46:47], v[88:89]
	v_pk_mul_f32 v[44:45], v[44:45], v[86:87]
	v_pk_mul_f32 v[54:55], v[54:55], v[88:89]
	v_pk_mul_f32 v[52:53], v[52:53], v[86:87]
	v_mfma_f32_16x16x16_bf16 v[56:59], v[68:69], v[76:77], v[44:47]
	v_mul_f32_e64 v50, v50, v88
	v_mul_f32_e64 v51, v51, v89
	v_pk_mul_f32 v[48:49], v[48:49], v[86:87]
	s_waitcnt lgkmcnt(0)
	v_pk_mul_f32 v[38:39], v[38:39], v[26:27]
	v_pk_mul_f32 v[36:37], v[36:37], v[24:25]
	v_pk_mul_f32 v[34:35], v[34:35], v[26:27]
	v_pk_mul_f32 v[32:33], v[32:33], v[24:25]
	v_pk_mul_f32 v[22:23], v[22:23], v[26:27]
	v_pk_mul_f32 v[20:21], v[20:21], v[24:25]
	v_mfma_f32_16x16x16_bf16 v[52:55], v[68:69], v[0:1], v[52:55]
	v_mfma_f32_16x16x16_bf16 v[48:51], v[68:69], v[72:73], v[48:51]
	v_mfma_f32_16x16x16_bf16 v[68:71], v[84:85], v[0:1], v[36:39]
	v_mfma_f32_16x16x16_bf16 v[72:75], v[84:85], v[72:73], v[32:35]
	v_mfma_f32_16x16x16_bf16 v[76:79], v[84:85], v[76:77], v[20:23]
	s_and_saveexec_b64 s[2:3], s[6:7]
	s_cbranch_execz .LBB0_590
; template <int MODE>
; __device__ void scan_unit(int swave, const Params& p, int j, int b, int h, int dir, char* shm) {
;     ...
;     bf16x8 Asc = {0, 0, 0, 0, 0, 0, 0, 0};
;     if (KS == 1 || wk == 0) {
;       f32x4 sc = {0.f, 0.f, 0.f, 0.f};
; #pragma unroll
;       for (int m = 0; m < DK / 32; ++m) {
;         const bf16x8 a = *(const bf16x8*)(ktil + r * QS + m * 32 + q4 * 8);
;         const bf16x8 bb = *(const bf16x8*)(qin + r * QS + m * 32 + q4 * 8);
;         sc = __builtin_amdgcn_mfma_f32_16x16x32_bf16(a, bb, sc, 0, 0, 0);
;       }
;       {
;         const unsigned p01 = pk2(q4 * 4 + 0 > r ? 0.f : sc[0], q4 * 4 + 1 > r ? 0.f : sc[1]);
;         const unsigned p23 = pk2(q4 * 4 + 2 > r ? 0.f : sc[2], q4 * 4 + 3 > r ? 0.f : sc[3]);
;         Asc[0] = (short)(p01 & 0xffff); Asc[1] = (short)(p01 >> 16); Asc[2] = (short)(p23 & 0xffff); Asc[3] = (short)(p23 >> 16);
;       }
;     }
;     bf16x8 Bv[NVT];
; #pragma unroll
;     for (int t = 0; t < NVT; ++t) {
;       const uint2 vv = *(const uint2*)(vT + ((vt0 + t) * 16 + r) * VS + q4 * 4);
;       Bv[t] = (bf16x8){(short)(vv.x & 0xffff), (short)(vv.x >> 16), (short)(vv.y & 0xffff), (short)(vv.y >> 16), 0, 0, 0, 0};
;     }
;     bf16x8 Aq[2];
; #pragma unroll
;     for (int m = 0; m < 2; ++m) {
;       const uint2 lo = *(const uint2*)(qin + r * QS + slab + (2 * m) * 16 + q4 * 4);
;       const uint2 hi = *(const uint2*)(qin + r * QS + slab + (2 * m + 1) * 16 + q4 * 4);
;       Aq[m] = (bf16x8){(short)(lo.x & 0xffff), (short)(lo.x >> 16), (short)(lo.y & 0xffff), (short)(lo.y >> 16),
;                        (short)(hi.x & 0xffff), (short)(hi.x >> 16), (short)(hi.y & 0xffff), (short)(hi.y >> 16)};
;     }
;     f32x4 o[NVT];
; #pragma unroll
;     for (int t = 0; t < NVT; ++t) {
;       o[t] = (f32x4){0.f, 0.f, 0.f, 0.f};
;       if (KS == 1 || wk == 0) o[t] = __builtin_amdgcn_mfma_f32_16x16x32_bf16(Asc, Bv[t], o[t], 0, 0, 0);
;     }
; #pragma unroll
;     for (int m = 0; m < 2; ++m)
; #pragma unroll
;       for (int t = 0; t < NVT; ++t) {
;         const f32x4 s0 = S[2 * m][t], s1 = S[2 * m + 1][t];
;         union { unsigned u[4]; bf16x8 v; } cv;
;         cv.u[0] = pk2(s0[0], s0[1]); cv.u[1] = pk2(s0[2], s0[3]); cv.u[2] = pk2(s1[0], s1[1]); cv.u[3] = pk2(s1[2], s1[3]);
;         o[t] = __builtin_amdgcn_mfma_f32_16x16x32_bf16(Aq[m], cv.v, o[t], 0, 0, 0);
;       }
; #pragma unroll
	s_nop 0
	ds_read_b128 v[20:23], v160 offset:25344
	ds_read_b128 v[24:27], v160 offset:20992
	ds_read_b128 v[84:87], v160 offset:25408
	ds_read_b128 v[88:91], v160 offset:21056
	ds_read_b128 v[32:35], v160 offset:25472
	s_pack_ll_b32_b16 s20, 0, 0
	s_waitcnt lgkmcnt(3)
	v_mfma_f32_16x16x32_bf16 v[20:23], v[20:23], v[24:27], 0
	ds_read_b128 v[24:27], v160 offset:21120
	s_waitcnt lgkmcnt(2)
	v_mfma_f32_16x16x32_bf16 v[20:23], v[84:87], v[88:91], v[20:23]
	ds_read_b128 v[84:87], v160 offset:25536
	ds_read_b128 v[88:91], v160 offset:21184
	s_waitcnt lgkmcnt(2)
	v_mfma_f32_16x16x32_bf16 v[20:23], v[32:35], v[24:27], v[20:23]
	s_waitcnt lgkmcnt(0)
	v_mfma_f32_16x16x32_bf16 v[20:23], v[84:87], v[88:91], v[20:23]
	s_nop 7
	v_cndmask_b32_e64 v0, v20, 0, s[8:9]
	v_cndmask_b32_e64 v1, 0, v21, s[10:11]
	v_cvt_pk_bf16_f32 v80, v0, v1
	v_cndmask_b32_e64 v0, v22, 0, s[12:13]
	v_cndmask_b32_e64 v1, v23, 0, s[14:15]
	v_cvt_pk_bf16_f32 v81, v0, v1
.LBB0_590:
	s_or_b64 exec, exec, s[2:3]
	ds_read_b64 v[0:1], v175 offset:33792
	ds_read_b64 v[88:89], v176 offset:33792
	ds_read_b64 v[84:85], v177 offset:33792
	v_add_u32_e32 v20, 0x5000, v224
	ds_read2_b64 v[24:27], v20 offset0:64 offset1:68
	ds_read2_b64 v[20:23], v20 offset0:72 offset1:76
	v_mov_b32_e32 v32, 0
	v_mov_b32_e32 v36, 0
	v_mov_b32_e32 v37, 0
	v_mov_b32_e32 v38, 0
	v_mov_b32_e32 v39, 0
	s_and_saveexec_b64 s[2:3], s[6:7]
	s_cbranch_execz .LBB0_592
	s_waitcnt lgkmcnt(4)
	v_mfma_f32_16x16x16_bf16 v[36:39], v[80:81], v[0:1], 0
.LBB0_592:
	s_or_b64 exec, exec, s[2:3]
	v_mov_b32_e32 v33, 0
	v_mov_b32_e32 v34, 0
	v_mov_b32_e32 v35, 0
	s_and_saveexec_b64 s[2:3], s[6:7]
	s_cbranch_execz .LBB0_594
	s_waitcnt lgkmcnt(3)
	v_mfma_f32_16x16x16_bf16 v[32:35], v[80:81], v[88:89], 0
.LBB0_594:
	s_or_b64 exec, exec, s[2:3]
	v_mov_b32_e32 v44, 0
	v_mov_b32_e32 v45, 0
	v_mov_b32_e32 v46, 0
	v_mov_b32_e32 v47, 0
	s_and_saveexec_b64 s[2:3], s[6:7]
	s_cbranch_execz .LBB0_596
	s_waitcnt lgkmcnt(2)
	v_mfma_f32_16x16x16_bf16 v[44:47], v[80:81], v[84:85], 0
.LBB0_596:
	s_or_b64 exec, exec, s[2:3]
	s_waitcnt lgkmcnt(1)
	v_bfi_b32 v26, s30, v26, v26
	s_waitcnt lgkmcnt(0)
	v_bfi_b32 v22, s30, v22, v22
	v_cvt_pk_bf16_f32 v80, v4, v5
	v_cvt_pk_bf16_f32 v81, v6, v7
	v_cvt_pk_bf16_f32 v82, v40, v41
	v_cvt_pk_bf16_f32 v83, v42, v43
	s_nop 1
	v_mfma_f32_16x16x32_bf16 v[36:39], v[24:27], v[80:83], v[36:39]
	v_cvt_pk_bf16_f32 v80, v8, v9
	v_cvt_pk_bf16_f32 v81, v10, v11
	v_cvt_pk_bf16_f32 v82, v60, v61
	v_cvt_pk_bf16_f32 v83, v62, v63
	s_nop 1
	v_mfma_f32_16x16x32_bf16 v[32:35], v[24:27], v[80:83], v[32:35]
	v_cvt_pk_bf16_f32 v80, v28, v29
	v_cvt_pk_bf16_f32 v81, v30, v31
	v_cvt_pk_bf16_f32 v82, v64, v65
	v_cvt_pk_bf16_f32 v83, v66, v67
	s_nop 1
	v_mfma_f32_16x16x32_bf16 v[24:27], v[24:27], v[80:83], v[44:47]
	s_nop 2
	v_cvt_pk_bf16_f32 v44, v52, v53
	v_cvt_pk_bf16_f32 v45, v54, v55
	v_cvt_pk_bf16_f32 v46, v68, v69
	v_cvt_pk_bf16_f32 v47, v70, v71
	s_nop 1
	v_mfma_f32_16x16x32_bf16 v[36:39], v[20:23], v[44:47], v[36:39]
	v_cvt_pk_bf16_f32 v44, v48, v49
	v_cvt_pk_bf16_f32 v45, v50, v51
	v_cvt_pk_bf16_f32 v46, v72, v73
	v_cvt_pk_bf16_f32 v47, v74, v75
	s_nop 1
	v_mfma_f32_16x16x32_bf16 v[32:35], v[20:23], v[44:47], v[32:35]
	v_cvt_pk_bf16_f32 v44, v56, v57
	v_cvt_pk_bf16_f32 v45, v58, v59
	v_cvt_pk_bf16_f32 v46, v76, v77
	v_cvt_pk_bf16_f32 v47, v78, v79
	s_nop 1
	v_mfma_f32_16x16x32_bf16 v[20:23], v[20:23], v[44:47], v[24:27]
	s_nop 2
	v_cvt_pk_bf16_f32 v24, v36, s0
	ds_write_b16 v178, v24
	v_cvt_pk_bf16_f32 v24, v37, s0
	ds_write_b16 v179, v24
	v_cvt_pk_bf16_f32 v24, v38, s0
	ds_write_b16 v180, v24
	v_cvt_pk_bf16_f32 v24, v39, s0
	ds_write_b16 v181, v24
	v_cvt_pk_bf16_f32 v24, v32, s0
	ds_write_b16 v182, v24
	v_cvt_pk_bf16_f32 v24, v33, s0
	ds_write_b16 v183, v24
	v_cvt_pk_bf16_f32 v24, v34, s0
	ds_write_b16 v184, v24
	v_cvt_pk_bf16_f32 v24, v35, s0
	v_cvt_pk_bf16_f32 v20, v20, s0
	ds_write_b16 v185, v24
	ds_write_b16 v186, v20
	v_cvt_pk_bf16_f32 v20, v21, s0
	ds_write_b16 v187, v20
	v_cvt_pk_bf16_f32 v20, v22, s0
	ds_write_b16 v188, v20
	v_cvt_pk_bf16_f32 v20, v23, s0
	ds_write_b16 v189, v20
	ds_read2st64_b64 v[32:35], v173 offset0:58 offset1:59
	ds_read2st64_b64 v[80:83], v173 offset0:60 offset1:61
	ds_read_b128 v[44:47], v190 offset:41472
	ds_read_b128 v[236:239], v190 offset:41536
	s_waitcnt lgkmcnt(3)
	s_waitcnt lgkmcnt(1)
	v_pk_mul_f32 v[6:7], v[6:7], v[46:47]
	v_pk_mul_f32 v[4:5], v[4:5], v[44:45]
	s_nop 1
	v_mfma_f32_16x16x16_bf16 v[20:23], v[32:33], v[0:1], v[4:7]
	s_nop 2
	v_mul_f32_e64 v6, v10, v46
	v_mul_f32_e64 v7, v11, v47
	v_pk_mul_f32 v[4:5], v[8:9], v[44:45]
	s_waitcnt lgkmcnt(0)
	v_pk_mul_f32 v[10:11], v[42:43], v[238:239]
	v_pk_mul_f32 v[8:9], v[40:41], v[236:237]
	v_mfma_f32_16x16x16_bf16 v[24:27], v[32:33], v[88:89], v[4:7]
	s_nop 2
	v_mul_f32_e64 v6, v30, v46
	v_mul_f32_e64 v7, v31, v47
	v_pk_mul_f32 v[4:5], v[28:29], v[44:45]
	s_nop 1
	v_mfma_f32_16x16x16_bf16 v[28:31], v[32:33], v[84:85], v[4:7]
	s_nop 2
	v_mov_b32_e32 v4, v34
	v_mov_b32_e32 v5, v35
	s_nop 1
	v_mfma_f32_16x16x16_bf16 v[32:35], v[4:5], v[0:1], v[8:11]
	s_nop 2
	v_mul_f32_e64 v10, v62, v238
	v_mul_f32_e64 v11, v63, v239
	v_pk_mul_f32 v[8:9], v[60:61], v[236:237]
	s_nop 1
	v_mfma_f32_16x16x16_bf16 v[36:39], v[4:5], v[88:89], v[8:11]
	s_nop 0
	s_nop 1
	v_pk_mul_f32 v[10:11], v[66:67], v[238:239]
	v_pk_mul_f32 v[8:9], v[64:65], v[236:237]
	ds_read_b128 v[236:239], v190 offset:41600
	s_nop 0
	v_mfma_f32_16x16x16_bf16 v[64:67], v[4:5], v[84:85], v[8:11]
	ds_read_b128 v[4:7], v190 offset:41664
	s_waitcnt lgkmcnt(0)
	s_barrier
; __device__ __forceinline__ unsigned pk2(float lo, float hi) { f32x2_t v = {lo, hi}; bf16x2_t b = __builtin_convertvector(v, bf16x2_t); return __builtin_bit_cast(unsigned, b); }
; __device__ __forceinline__ float lo_bf(unsigned u) { return __uint_as_float(u << 16); }
; __device__ __forceinline__ float hi_bf(unsigned u) { return __uint_as_float(u & 0xffff0000u); }
; template <int MODE>
; __device__ void scan_unit(int swave, const Params& p, int j, int b, int h, int dir, char* shm) {
;     ...
;   auto load_raw = [&](int c, Raw& R) {
;     const int tok = tokof(c, ti);
;     const bf16_t* row = P + (rowbase + tok) * LDP;
;     if (MODE == 0) {
;       R.q = *(const unsigned*)(row + E_GQ + h * 64 + dp); R.k = *(const unsigned*)(row + E_GK + h * 64 + dp);
;       const uint4* lrp = (const uint4*)(row + (dir ? E_GLB : E_GLF));
;       R.lr0 = lrp[0]; R.lr1 = lrp[1];
;       R.v = *(const uint2*)(row + E_GV + h * 128 + vg * 4);
;     } else if (MODE == 1) {
;       R.q = *(const unsigned*)(row + E_HQ + h * 64 + dp); R.k = *(const unsigned*)(row + (dir ? E_HZB : E_HZF) + h * 64 + dp);
;       R.v = *(const uint2*)(row + E_HI + h * 128 + vg * 4);
;     } else {
;       R.q = *(const unsigned*)(row + O_RQ + h * 128 + dp); R.q2 = *(const unsigned*)(row + O_RQ + h * 128 + 64 + dp);
;       R.k = *(const unsigned*)(row + O_RK + h * 128 + dp); R.k2 = *(const unsigned*)(row + O_RK + h * 128 + 64 + dp);
;       R.cs = *(const float4*)(rope + tok * 64 + dp);
;       const unsigned* vp = (const unsigned*)(row + O_RV + h * 192 + vg * 6);
;       R.v30 = vp[0]; R.v31 = vp[1]; R.v32 = vp[2];
;     }
;     ...
; #pragma unroll
;       for (int t = 0; t < NVT; ++t) S[kt][t] = __builtin_amdgcn_mfma_f32_16x16x32_bf16(Ak, Bv[t], S[kt][t] * dc, 0, 0, 0);
;     ...
;   auto ostore = [&](int c, const bf16_t* obuf) {
;     for (int idx = tid; idx < 16 * DV / 4; idx += 512) {
;       const int i = idx / (DV / 4), cc = (idx % (DV / 4)) * 4;
;       uint2 o = *(const uint2*)(obuf + i * OS + cc);
;       if (KS == 2) {
;         const uint2 o2 = *(const uint2*)(obuf + (16 + i) * OS + cc);
;         o.x = pk2(lo_bf(o.x) + lo_bf(o2.x), hi_bf(o.x) + hi_bf(o2.x)); o.y = pk2(lo_bf(o.y) + lo_bf(o2.y), hi_bf(o.y) + hi_bf(o2.y));
;       }
;       *(uint2*)(O + (rowbase + tokof(c, i)) * OLD + cc) = o;
;     }
	s_waitcnt vmcnt(6)
	s_waitcnt lgkmcnt(1)
	v_pk_mul_f32 v[10:11], v[54:55], v[238:239]
	v_pk_mul_f32 v[8:9], v[52:53], v[236:237]
	s_waitcnt lgkmcnt(0)
	v_pk_mul_f32 v[54:55], v[70:71], v[6:7]
	v_pk_mul_f32 v[52:53], v[68:69], v[4:5]
	v_mfma_f32_16x16x16_bf16 v[40:43], v[80:81], v[0:1], v[8:11]
	s_waitcnt vmcnt(0)
	s_nop 1
	v_pk_mul_f32 v[10:11], v[50:51], v[238:239]
	v_pk_mul_f32 v[8:9], v[48:49], v[236:237]
	s_nop 1
	v_mfma_f32_16x16x16_bf16 v[44:47], v[80:81], v[88:89], v[8:11]
	s_nop 2
	v_mul_f32_e64 v10, v58, v238
	v_mul_f32_e64 v11, v59, v239
	v_pk_mul_f32 v[8:9], v[56:57], v[236:237]
	v_pk_mul_f32 v[58:59], v[74:75], v[6:7]
	v_pk_mul_f32 v[56:57], v[72:73], v[4:5]
	v_mfma_f32_16x16x16_bf16 v[48:51], v[80:81], v[84:85], v[8:11]
	v_mul_f32_e64 v6, v78, v6
	v_mul_f32_e64 v7, v79, v7
	v_pk_mul_f32 v[4:5], v[76:77], v[4:5]
	s_nop 1
	v_mfma_f32_16x16x16_bf16 v[52:55], v[82:83], v[0:1], v[52:55]
	v_mfma_f32_16x16x16_bf16 v[56:59], v[82:83], v[88:89], v[56:59]
	v_mfma_f32_16x16x16_bf16 v[60:63], v[82:83], v[84:85], v[4:7]
	s_add_i32 s20, s25, 0x60
	s_and_b64 s[2:3], s[68:69], exec
	s_cselect_b32 s2, s20, 0x7e0
	v_or_b32_e32 v2, s2, v116
	v_sub_u32_e32 v0, 0x7ff, v2
	v_cndmask_b32_e64 v0, v0, v2, s[0:1]
	v_ashrrev_i32_e32 v1, 31, v0
	v_lshl_add_u64 v[4:5], s[18:19], 0, v[0:1]
	v_mov_b64_e32 v[6:7], s[44:45]
	v_mad_u64_u32 v[8:9], s[2:3], v4, s55, v[6:7]
	v_mad_i32_i24 v9, v5, s55, v9
	v_lshl_add_u64 v[4:5], v[8:9], 0, s[94:95]
	v_lshlrev_b32_e32 v0, 6, v0
	v_lshl_add_u64 v[4:5], v[4:5], 0, v[118:119]
	v_ashrrev_i32_e32 v1, 31, v0
	s_mov_b32 s47, s95
	global_load_dword v242, v[4:5], off
	global_load_dword v241, v[4:5], off offset:128
	global_load_dword v240, v[4:5], off offset:1024
	global_load_dword v239, v[4:5], off offset:1152
	v_lshl_add_u64 v[0:1], v[0:1], 3, v[130:131]
	v_lshl_add_u64 v[4:5], v[8:9], 0, s[46:47]
	v_lshl_add_u64 v[4:5], v[4:5], 0, v[122:123]
	global_load_dwordx4 v[8:11], v[0:1], off
	global_load_dwordx3 v[112:114], v[4:5], off offset:2048
	v_or_b32_e32 v0, 16, v2
	v_sub_u32_e32 v1, 0x7ff, v0
	v_cndmask_b32_e64 v0, v1, v0, s[0:1]
	v_ashrrev_i32_e32 v1, 31, v0
	v_lshl_add_u64 v[4:5], s[18:19], 0, v[0:1]
	v_mad_u64_u32 v[6:7], s[2:3], v4, s55, v[6:7]
	v_mad_i32_i24 v7, v5, s55, v7
	v_lshl_add_u64 v[4:5], v[6:7], 0, s[94:95]
	v_lshl_add_u64 v[4:5], v[4:5], 0, v[118:119]
	v_lshlrev_b32_e32 v0, 6, v0
	global_load_dword v238, v[4:5], off
	global_load_dword v237, v[4:5], off offset:128
	global_load_dword v236, v[4:5], off offset:1024
	global_load_dword v235, v[4:5], off offset:1152
	v_ashrrev_i32_e32 v1, 31, v0
	v_lshl_add_u64 v[0:1], v[0:1], 3, v[130:131]
	v_lshl_add_u64 v[4:5], v[6:7], 0, s[46:47]
	v_lshl_add_u64 v[68:69], v[4:5], 0, v[122:123]
	global_load_dwordx4 v[4:7], v[0:1], off
	global_load_dwordx3 v[108:110], v[68:69], off offset:2048
	s_and_saveexec_b64 s[2:3], s[4:5]
	s_movk_i32 s33, 0x600
	s_cbranch_execz .LBB0_601
	s_sub_i32 s34, 0x7f0, s25
	s_cmp_lg_u64 s[0:1], 0
	s_cselect_b32 s34, s25, s34
	s_add_i32 s34, s34, s18
	s_mul_i32 s35, s34, 0x600
	s_add_u32 s28, s42, s35
	s_addc_u32 s29, s43, 0
	v_add_u32_e32 v2, v225, v243
	v_add_u32_e32 v78, v225, v244
	ds_read_b64 v[70:71], v2
	ds_read_b64 v[72:73], v2 offset:6272
	ds_read_b64 v[0:1], v78
	ds_read_b64 v[68:69], v78 offset:6272
	s_waitcnt lgkmcnt(2)
	v_lshlrev_b32_e32 v74, 16, v70
	v_lshlrev_b32_e32 v76, 16, v72
	v_and_b32_e32 v75, 0xffff0000, v70
	v_and_b32_e32 v77, 0xffff0000, v72
	v_pk_add_f32 v[74:75], v[74:75], v[76:77]
	v_lshlrev_b32_e32 v76, 16, v73
	v_and_b32_e32 v77, 0xffff0000, v73
	v_cvt_pk_bf16_f32 v70, v74, v75
	v_lshlrev_b32_e32 v74, 16, v71
	v_and_b32_e32 v75, 0xffff0000, v71
	v_pk_add_f32 v[74:75], v[74:75], v[76:77]
	s_nop 0
	v_cvt_pk_bf16_f32 v71, v74, v75
	s_nop 0
	global_store_dwordx2 v249, v[70:71], s[28:29]
	v_cmp_gt_u32_e32 vcc, 0x100, v111
	s_and_saveexec_b64 s[34:35], vcc
	s_cbranch_execz .Lros_skip_c
	s_waitcnt lgkmcnt(0)
	v_lshlrev_b32_e32 v74, 16, v0
	v_lshlrev_b32_e32 v76, 16, v68
	v_and_b32_e32 v75, 0xffff0000, v0
	v_and_b32_e32 v77, 0xffff0000, v68
	v_pk_add_f32 v[74:75], v[74:75], v[76:77]
	v_lshlrev_b32_e32 v76, 16, v69
	v_and_b32_e32 v77, 0xffff0000, v69
	v_cvt_pk_bf16_f32 v0, v74, v75
	v_lshlrev_b32_e32 v74, 16, v1
	v_and_b32_e32 v75, 0xffff0000, v1
	v_pk_add_f32 v[74:75], v[74:75], v[76:77]
	s_nop 0
	v_cvt_pk_bf16_f32 v1, v74, v75
	s_nop 0
	global_store_dwordx2 v250, v[0:1], s[28:29]

; template <int MODE>
; __device__ void scan_unit(int swave, const Params& p, int j, int b, int h, int dir, char* shm) {
;     ...
;       const float KSC = 0.08838834764831845f;
;       const float qx0 = lo_bf(R.q), qx1 = hi_bf(R.q), qy0 = lo_bf(R.q2), qy1 = hi_bf(R.q2);
;       const float kx0 = lo_bf(R.k) * KSC, kx1 = hi_bf(R.k) * KSC, ky0 = lo_bf(R.k2) * KSC, ky1 = hi_bf(R.k2) * KSC;
;       const float c0 = R.cs.x, sn0 = R.cs.y, c1 = R.cs.z, sn1 = R.cs.w;
;       const float qa0 = qx0 * c0 - qy0 * sn0, qb0 = qx0 * sn0 + qy0 * c0, qa1 = qx1 * c1 - qy1 * sn1, qb1 = qx1 * sn1 + qy1 * c1;
;       const float ka0 = kx0 * c0 - ky0 * sn0, kb0 = kx0 * sn0 + ky0 * c0, ka1 = kx1 * c1 - ky1 * sn1, kb1 = kx1 * sn1 + ky1 * c1;
;       const float ein = ret_ein, eti = ret_eti, eout = ret_eout;
;       *(unsigned*)(qin + ti * QS + dp) = pk2(qa0 * ein, qa1 * ein); *(unsigned*)(qin + ti * QS + 64 + dp) = pk2(qb0 * ein, qb1 * ein);
;       *(unsigned*)(ktil + ti * QS + dp) = pk2(ka0 * eti, ka1 * eti); *(unsigned*)(ktil + ti * QS + 64 + dp) = pk2(kb0 * eti, kb1 * eti);
;       koutT[dp * 16 + ti] = f2bf(ka0 * eout); koutT[(dp + 1) * 16 + ti] = f2bf(ka1 * eout);
;       koutT[(64 + dp) * 16 + ti] = f2bf(kb0 * eout); koutT[(65 + dp) * 16 + ti] = f2bf(kb1 * eout);
;       if (ti == 0) { const float dd = ret_dd; *(float2*)(dec + dp) = make_float2(dd, dd); *(float2*)(dec + 64 + dp) = make_float2(dd, dd); }
;       const int c6 = vg * 6;
;       vT[(c6 + 0) * VS + ti] = (bf16_t)(R.v30 & 0xffff); vT[(c6 + 1) * VS + ti] = (bf16_t)(R.v30 >> 16);
;       vT[(c6 + 2) * VS + ti] = (bf16_t)(R.v31 & 0xffff); vT[(c6 + 3) * VS + ti] = (bf16_t)(R.v31 >> 16);
;       vT[(c6 + 4) * VS + ti] = (bf16_t)(R.v32 & 0xffff); vT[(c6 + 5) * VS + ti] = (bf16_t)(R.v32 >> 16);
;     }
;   };
;   f32x4 S[4][NVT];
; #pragma unroll
;   for (int a = 0; a < 4; ++a)
; #pragma unroll
;     for (int t = 0; t < NVT; ++t) S[a][t] = (f32x4){0.f, 0.f, 0.f, 0.f};
;   auto compute = [&](const char* buf, bf16_t* obuf) {
;     const bf16_t* qin = (const bf16_t*)buf; const bf16_t* ktil = (const bf16_t*)(buf + OFF_KT); const bf16_t* koutT = (const bf16_t*)(buf + OFF_KO);
;     const bf16_t* vT = (const bf16_t*)(buf + OFF_VT); const float* dec = (const float*)(buf + OFF_DEC);
;     bf16x8 Asc = {0, 0, 0, 0, 0, 0, 0, 0};
;     if (KS == 1 || wk == 0) {
;       f32x4 sc = {0.f, 0.f, 0.f, 0.f};
; #pragma unroll
.LBB0_601:
	s_or_b64 exec, exec, s[2:3]
	v_lshlrev_b32_e32 v68, 16, v106
	v_and_b32_e32 v69, 0xffff0000, v106
	v_mov_b32_e32 v75, v18
	v_mov_b32_e32 v18, v17
	v_lshlrev_b32_e32 v0, 16, v107
	v_and_b32_e32 v1, 0xffff0000, v107
	v_mov_b32_e32 v74, v16
	v_pk_mul_f32 v[16:17], v[18:19], v[68:69]
	v_lshlrev_b32_e32 v72, 16, v104
	v_pk_fma_f32 v[16:17], v[74:75], v[0:1], v[16:17] neg_lo:[0,0,1] neg_hi:[0,0,1]
	v_pk_mul_f32 v[0:1], v[18:19], v[0:1]
	v_and_b32_e32 v73, 0xffff0000, v104
	v_pk_fma_f32 v[0:1], v[74:75], v[68:69], v[0:1]
	v_pk_mul_f32 v[16:17], v[124:125], v[16:17]
	v_pk_mul_f32 v[0:1], v[124:125], v[0:1]
	s_mov_b32 s2, 0x3db504f3
	v_lshlrev_b32_e32 v70, 16, v105
	v_and_b32_e32 v71, 0xffff0000, v105
	v_cvt_pk_bf16_f32 v2, v16, v17
	v_cvt_pk_bf16_f32 v0, v0, v1
	v_pk_mul_f32 v[16:17], v[72:73], s[2:3] op_sel_hi:[1,0]
	ds_write2_b32 v121, v2, v0 offset1:32
	v_pk_mul_f32 v[0:1], v[70:71], s[2:3] op_sel_hi:[1,0]
	v_pk_mul_f32 v[68:69], v[18:19], v[16:17]
	s_nop 0
	v_pk_fma_f32 v[68:69], v[74:75], v[0:1], v[68:69] neg_lo:[0,0,1] neg_hi:[0,0,1]
	v_pk_mul_f32 v[0:1], v[0:1], v[18:19]
	v_pk_mul_f32 v[70:71], v[126:127], v[68:69]
	v_pk_fma_f32 v[0:1], v[16:17], v[74:75], v[0:1]
	v_cvt_pk_bf16_f32 v2, v70, v71
	v_pk_mul_f32 v[16:17], v[126:127], v[0:1]
	v_mul_f32_e32 v0, v117, v0
	v_cvt_pk_bf16_f32 v16, v16, v17
	ds_write2_b32 v135, v2, v16 offset0:64 offset1:96
	v_mul_f32_e32 v2, v117, v68
	v_cvt_pk_bf16_f32 v2, v2, s0
	v_cvt_pk_bf16_f32 v0, v0, s0
	ds_write_b16 v136, v2 offset:8704
	v_mul_f32_e32 v2, v117, v69
	ds_write_b16 v136, v0 offset:10752
	v_mul_f32_e32 v0, v117, v1
	v_cvt_pk_bf16_f32 v2, v2, s0
	v_cvt_pk_bf16_f32 v0, v0, s0
	ds_write_b16 v136, v2 offset:8736
	ds_write_b16 v136, v0 offset:10784
	s_and_saveexec_b64 s[2:3], s[16:17]
	v_add_u32_e32 v0, 0x5000, v141
	ds_write2_b64 v0, v[128:129], v[128:129] offset1:32
	s_or_b64 exec, exec, s[2:3]
	v_lshlrev_b32_e32 v16, 16, v102
	v_and_b32_e32 v17, 0xffff0000, v102
	v_mov_b32_e32 v71, v14
	v_mov_b32_e32 v14, v13
	v_lshlrev_b32_e32 v0, 16, v103
	v_and_b32_e32 v1, 0xffff0000, v103
	v_mov_b32_e32 v70, v12
	v_pk_mul_f32 v[12:13], v[14:15], v[16:17]
	v_lshlrev_b32_e32 v68, 16, v97
	v_pk_fma_f32 v[12:13], v[70:71], v[0:1], v[12:13] neg_lo:[0,0,1] neg_hi:[0,0,1]
	v_pk_mul_f32 v[0:1], v[14:15], v[0:1]
	v_and_b32_e32 v69, 0xffff0000, v97
	v_pk_fma_f32 v[0:1], v[70:71], v[16:17], v[0:1]
	v_pk_mul_f32 v[12:13], v[124:125], v[12:13]
	v_pk_mul_f32 v[0:1], v[124:125], v[0:1]
	s_mov_b32 s2, 0x3db504f3
	v_lshlrev_b32_e32 v18, 16, v101
	v_and_b32_e32 v19, 0xffff0000, v101
	v_cvt_pk_bf16_f32 v2, v12, v13
	v_cvt_pk_bf16_f32 v0, v0, v1
	v_pk_mul_f32 v[12:13], v[68:69], s[2:3] op_sel_hi:[1,0]
	ds_write_b16 v137, v98 offset:12800
	ds_write_b16_d16_hi v137, v98 offset:12840
	ds_write_b16 v137, v99 offset:12880
	ds_write_b16_d16_hi v137, v99 offset:12920
	ds_write_b16 v137, v100 offset:12960
	ds_write_b16_d16_hi v137, v100 offset:13000
	ds_write2_b32 v139, v2, v0 offset0:128 offset1:160
	v_pk_mul_f32 v[0:1], v[18:19], s[2:3] op_sel_hi:[1,0]
	v_pk_mul_f32 v[16:17], v[14:15], v[12:13]
	s_nop 0
	v_pk_fma_f32 v[16:17], v[70:71], v[0:1], v[16:17] neg_lo:[0,0,1] neg_hi:[0,0,1]
	v_pk_mul_f32 v[0:1], v[0:1], v[14:15]
	v_pk_mul_f32 v[18:19], v[126:127], v[16:17]
	v_pk_fma_f32 v[0:1], v[12:13], v[70:71], v[0:1]
	v_cvt_pk_bf16_f32 v2, v18, v19
	v_pk_mul_f32 v[12:13], v[126:127], v[0:1]
	v_mul_f32_e32 v0, v117, v0
	v_cvt_pk_bf16_f32 v12, v12, v13
	ds_write2_b32 v140, v2, v12 offset0:192 offset1:224
	v_mul_f32_e32 v2, v117, v16
	v_cvt_pk_bf16_f32 v2, v2, s0
	v_cvt_pk_bf16_f32 v0, v0, s0
	ds_write_b16 v136, v2 offset:29696
	v_mul_f32_e32 v2, v117, v17
	ds_write_b16 v136, v0 offset:31744
	v_mul_f32_e32 v0, v117, v1
	v_cvt_pk_bf16_f32 v2, v2, s0
	v_cvt_pk_bf16_f32 v0, v0, s0
	ds_write_b16 v136, v2 offset:29728
	ds_write_b16 v136, v0 offset:31776
	s_and_saveexec_b64 s[2:3], s[16:17]
	v_add_u32_e32 v0, 0xa000, v141
	ds_write2_b64 v0, v[128:129], v[128:129] offset0:64 offset1:96
	s_or_b64 exec, exec, s[2:3]
	v_mov_b32_e32 v12, 0
	v_mov_b32_e32 v68, 0
	v_mov_b32_e32 v69, 0
	ds_write_b16 v137, v94 offset:33792
	ds_write_b16_d16_hi v137, v94 offset:33832
	ds_write_b16 v137, v95 offset:33872
	ds_write_b16_d16_hi v137, v95 offset:33912
	ds_write_b16 v137, v96 offset:33952
	ds_write_b16_d16_hi v137, v96 offset:33992
	s_and_saveexec_b64 s[2:3], s[6:7]
	s_cbranch_execz .LBB0_607
	ds_read_b128 v[14:17], v160 offset:46336
	ds_read_b128 v[68:71], v160 offset:41984
	ds_read_b128 v[76:79], v160 offset:46400
	ds_read_b128 v[80:83], v160 offset:42048
	ds_read_b128 v[72:75], v160 offset:46464
	s_pack_ll_b32_b16 s20, 0, 0
	s_waitcnt lgkmcnt(3)
	v_mfma_f32_16x16x32_bf16 v[14:17], v[14:17], v[68:71], 0
	ds_read_b128 v[68:71], v160 offset:42112
	s_waitcnt lgkmcnt(2)
	v_mfma_f32_16x16x32_bf16 v[14:17], v[76:79], v[80:83], v[14:17]
	ds_read_b128 v[76:79], v160 offset:46528
	ds_read_b128 v[80:83], v160 offset:42176
	s_waitcnt lgkmcnt(2)
	v_mfma_f32_16x16x32_bf16 v[14:17], v[72:75], v[68:71], v[14:17]
	s_waitcnt lgkmcnt(0)
	v_mfma_f32_16x16x32_bf16 v[14:17], v[76:79], v[80:83], v[14:17]
	s_nop 5
	s_nop 1
	v_cndmask_b32_e64 v0, v14, 0, s[8:9]
	v_cndmask_b32_e64 v1, 0, v15, s[10:11]
	v_cvt_pk_bf16_f32 v68, v0, v1
	v_cndmask_b32_e64 v0, v16, 0, s[12:13]
	v_cndmask_b32_e64 v1, v17, 0, s[14:15]
	v_cvt_pk_bf16_f32 v69, v0, v1
.LBB0_607:
	s_or_b64 exec, exec, s[2:3]
	ds_read_b64 v[0:1], v175 offset:54784
	ds_read_b64 v[76:77], v176 offset:54784
	ds_read_b64 v[72:73], v177 offset:54784
	v_add_u32_e32 v13, 0xa000, v224
	ds_read2_b64 v[80:83], v13 offset0:128 offset1:132
	ds_read2_b64 v[16:19], v13 offset0:136 offset1:140
	v_mov_b32_e32 v86, 0
	v_mov_b32_e32 v87, 0
	v_mov_b32_e32 v88, 0
	v_mov_b32_e32 v89, 0
	s_and_saveexec_b64 s[2:3], s[6:7]
	s_cbranch_execz .LBB0_609
	s_waitcnt lgkmcnt(4)
	v_mfma_f32_16x16x16_bf16 v[86:89], v[68:69], v[0:1], 0
; __device__ __forceinline__ bf16_t f2bf(float f) { return (bf16_t)(pk2(f, 0.f) & 0xffffu); }
; template <int MODE>
; __device__ void scan_unit(int swave, const Params& p, int j, int b, int h, int dir, char* shm) {
;     ...
;     bf16x8 Bv[NVT];
; #pragma unroll
;     for (int t = 0; t < NVT; ++t) {
;       const uint2 vv = *(const uint2*)(vT + ((vt0 + t) * 16 + r) * VS + q4 * 4);
;       Bv[t] = (bf16x8){(short)(vv.x & 0xffff), (short)(vv.x >> 16), (short)(vv.y & 0xffff), (short)(vv.y >> 16), 0, 0, 0, 0};
;     }
;     bf16x8 Aq[2];
; #pragma unroll
;     for (int m = 0; m < 2; ++m) {
;       const uint2 lo = *(const uint2*)(qin + r * QS + slab + (2 * m) * 16 + q4 * 4);
;       const uint2 hi = *(const uint2*)(qin + r * QS + slab + (2 * m + 1) * 16 + q4 * 4);
;       Aq[m] = (bf16x8){(short)(lo.x & 0xffff), (short)(lo.x >> 16), (short)(lo.y & 0xffff), (short)(lo.y >> 16),
;                        (short)(hi.x & 0xffff), (short)(hi.x >> 16), (short)(hi.y & 0xffff), (short)(hi.y >> 16)};
;     }
;     f32x4 o[NVT];
; #pragma unroll
;     for (int t = 0; t < NVT; ++t) {
;       o[t] = (f32x4){0.f, 0.f, 0.f, 0.f};
;       if (KS == 1 || wk == 0) o[t] = __builtin_amdgcn_mfma_f32_16x16x32_bf16(Asc, Bv[t], o[t], 0, 0, 0);
;     }
; #pragma unroll
;     for (int m = 0; m < 2; ++m)
; #pragma unroll
;       for (int t = 0; t < NVT; ++t) {
;         const f32x4 s0 = S[2 * m][t], s1 = S[2 * m + 1][t];
;         union { unsigned u[4]; bf16x8 v; } cv;
;         cv.u[0] = pk2(s0[0], s0[1]); cv.u[1] = pk2(s0[2], s0[3]); cv.u[2] = pk2(s1[0], s1[1]); cv.u[3] = pk2(s1[2], s1[3]);
;         o[t] = __builtin_amdgcn_mfma_f32_16x16x32_bf16(Aq[m], cv.v, o[t], 0, 0, 0);
;       }
; #pragma unroll
;     for (int t = 0; t < NVT; ++t)
; #pragma unroll
;       for (int jj = 0; jj < 4; ++jj) obuf[(wk * 16 + q4 * 4 + jj) * OS + (vt0 + t) * 16 + r] = f2bf(o[t][jj]);
; #pragma unroll
;     for (int kt = 0; kt < 4; ++kt) {
;       const uint2 kk = *(const uint2*)(koutT + (slab + kt * 16 + r) * 16 + q4 * 4);
;       const bf16x8 Ak = {(short)(kk.x & 0xffff), (short)(kk.x >> 16), (short)(kk.y & 0xffff), (short)(kk.y >> 16), 0, 0, 0, 0};
;       const f32x4 dc = *(const f32x4*)(dec + slab + kt * 16 + q4 * 4);
; #pragma unroll
;       for (int t = 0; t < NVT; ++t) S[kt][t] = __builtin_amdgcn_mfma_f32_16x16x32_bf16(Ak, Bv[t], S[kt][t] * dc, 0, 0, 0);
;     }
.LBB0_609:
	s_or_b64 exec, exec, s[2:3]
	v_mov_b32_e32 v13, 0
	v_mov_b32_e32 v14, 0
	v_mov_b32_e32 v15, 0
	s_and_saveexec_b64 s[2:3], s[6:7]
	s_cbranch_execz .LBB0_611
	s_waitcnt lgkmcnt(3)
	v_mfma_f32_16x16x16_bf16 v[12:15], v[68:69], v[76:77], 0
.LBB0_611:
	s_or_b64 exec, exec, s[2:3]
	v_mov_b32_e32 v84, 0
	v_mov_b32_e32 v90, 0
	v_mov_b32_e32 v91, 0
	v_mov_b32_e32 v92, 0
	v_mov_b32_e32 v93, 0
	s_and_saveexec_b64 s[2:3], s[6:7]
	s_cbranch_execz .LBB0_613
	s_waitcnt lgkmcnt(2)
	v_mfma_f32_16x16x16_bf16 v[90:93], v[68:69], v[72:73], 0
.LBB0_613:
	s_or_b64 exec, exec, s[2:3]
	s_waitcnt lgkmcnt(1)
	v_bfi_b32 v82, s30, v82, v82
	s_waitcnt lgkmcnt(0)
	v_bfi_b32 v18, s30, v18, v18
	v_cvt_pk_bf16_f32 v68, v20, v21
	v_cvt_pk_bf16_f32 v69, v22, v23
	v_cvt_pk_bf16_f32 v70, v32, v33
	v_cvt_pk_bf16_f32 v71, v34, v35
	v_mov_b32_e32 v85, 0
	s_nop 0
	v_mfma_f32_16x16x32_bf16 v[68:71], v[80:83], v[68:71], v[86:89]
	s_nop 2
	v_cvt_pk_bf16_f32 v86, v24, v25
	v_cvt_pk_bf16_f32 v87, v26, v27
	v_cvt_pk_bf16_f32 v88, v36, v37
	v_cvt_pk_bf16_f32 v89, v38, v39
	s_nop 1
	v_mfma_f32_16x16x32_bf16 v[12:15], v[80:83], v[86:89], v[12:15]
	v_cvt_pk_bf16_f32 v86, v28, v29
	v_cvt_pk_bf16_f32 v87, v30, v31
	v_cvt_pk_bf16_f32 v88, v64, v65
	v_cvt_pk_bf16_f32 v89, v66, v67
	s_nop 1
	v_mfma_f32_16x16x32_bf16 v[80:83], v[80:83], v[86:89], v[90:93]
	v_cvt_pk_bf16_f32 v86, v40, v41
	v_cvt_pk_bf16_f32 v87, v42, v43
	v_cvt_pk_bf16_f32 v88, v52, v53
	v_cvt_pk_bf16_f32 v89, v54, v55
	s_nop 1
	v_mfma_f32_16x16x32_bf16 v[68:71], v[16:19], v[86:89], v[68:71]
	v_cvt_pk_bf16_f32 v86, v44, v45
	v_cvt_pk_bf16_f32 v87, v46, v47
	v_cvt_pk_bf16_f32 v88, v56, v57
	v_cvt_pk_bf16_f32 v89, v58, v59
	s_nop 1
	v_mfma_f32_16x16x32_bf16 v[12:15], v[16:19], v[86:89], v[12:15]
	s_nop 0
	v_cvt_pk_bf16_f32 v68, v68, s0
	ds_write_b16 v191, v68
	v_cvt_pk_bf16_f32 v68, v69, s0
	v_cvt_pk_bf16_f32 v86, v48, v49
	v_cvt_pk_bf16_f32 v87, v50, v51
	v_cvt_pk_bf16_f32 v88, v60, v61
	v_cvt_pk_bf16_f32 v89, v62, v63
	ds_write_b16 v192, v68
	v_cvt_pk_bf16_f32 v68, v70, s0
	v_mfma_f32_16x16x32_bf16 v[16:19], v[16:19], v[86:89], v[80:83]
	ds_write_b16 v193, v68
	v_cvt_pk_bf16_f32 v68, v71, s0
	v_cvt_pk_bf16_f32 v12, v12, s0
	ds_write_b16 v194, v68
	ds_write_b16 v195, v12
	v_cvt_pk_bf16_f32 v12, v13, s0
	ds_write_b16 v196, v12
	v_cvt_pk_bf16_f32 v12, v14, s0
	ds_write_b16 v197, v12
	v_cvt_pk_bf16_f32 v12, v15, s0
	ds_write_b16 v198, v12
	v_cvt_pk_bf16_f32 v12, v16, s0
	ds_write_b16 v199, v12
	v_cvt_pk_bf16_f32 v12, v17, s0
	ds_write_b16 v200, v12
	v_cvt_pk_bf16_f32 v12, v18, s0
	ds_write_b16 v201, v12
	v_cvt_pk_bf16_f32 v12, v19, s0
	ds_write_b16 v202, v12
	ds_read2st64_b64 v[12:15], v173 offset0:99 offset1:100
	ds_read2st64_b64 v[80:83], v173 offset0:101 offset1:102
	ds_read_b128 v[68:71], v190 offset:62464
	ds_read_b128 v[100:103], v190 offset:62528
	s_waitcnt lgkmcnt(3)
	v_mov_b32_e32 v16, v12
	v_mov_b32_e32 v17, v13
	s_waitcnt lgkmcnt(1)
	v_pk_mul_f32 v[22:23], v[22:23], v[70:71]
	v_pk_mul_f32 v[20:21], v[20:21], v[68:69]
	s_waitcnt lgkmcnt(0)
	v_pk_mul_f32 v[12:13], v[32:33], v[100:101]
	v_mfma_f32_16x16x16_bf16 v[96:99], v[16:17], v[0:1], v[20:23]
	s_nop 1
	s_nop 0
	v_pk_mul_f32 v[22:23], v[26:27], v[70:71]
	v_pk_mul_f32 v[20:21], v[24:25], v[68:69]
	v_pk_mul_f32 v[26:27], v[66:67], v[102:103]
	v_pk_mul_f32 v[24:25], v[64:65], v[100:101]
	v_mfma_f32_16x16x16_bf16 v[92:95], v[16:17], v[76:77], v[20:23]
	s_nop 2
	v_mul_f32_e64 v22, v30, v70
	v_mul_f32_e64 v23, v31, v71
	v_pk_mul_f32 v[20:21], v[28:29], v[68:69]
	s_nop 1
	v_mfma_f32_16x16x16_bf16 v[88:91], v[16:17], v[72:73], v[20:23]
	v_mov_b32_e32 v16, v14
	v_mov_b32_e32 v17, v15
	v_pk_mul_f32 v[14:15], v[34:35], v[102:103]
	s_nop 1
	v_mfma_f32_16x16x16_bf16 v[20:23], v[16:17], v[0:1], v[12:15]
	s_nop 2
	v_mul_f32_e64 v14, v38, v102
	v_mul_f32_e64 v15, v39, v103
	v_pk_mul_f32 v[12:13], v[36:37], v[100:101]
	ds_read_b128 v[36:39], v190 offset:62592
	s_nop 0
	v_mfma_f32_16x16x16_bf16 v[12:15], v[16:17], v[76:77], v[12:15]
	v_mfma_f32_16x16x16_bf16 v[16:19], v[16:17], v[72:73], v[24:27]
	s_nop 2
	ds_read_b128 v[24:27], v190 offset:62656
	s_waitcnt lgkmcnt(1)
	v_pk_mul_f32 v[34:35], v[42:43], v[38:39]
	v_pk_mul_f32 v[32:33], v[40:41], v[36:37]
	s_waitcnt lgkmcnt(0)
	v_pk_mul_f32 v[42:43], v[54:55], v[26:27]
	v_mfma_f32_16x16x16_bf16 v[68:71], v[80:81], v[0:1], v[32:35]
	v_mul_f32_e64 v40, v52, v24
	v_mul_f32_e64 v41, v53, v25
	s_nop 0
	v_pk_mul_f32 v[34:35], v[46:47], v[38:39]
	v_pk_mul_f32 v[32:33], v[44:45], v[36:37]
	v_pk_mul_f32 v[38:39], v[50:51], v[38:39]
	v_pk_mul_f32 v[36:37], v[48:49], v[36:37]
	v_mfma_f32_16x16x16_bf16 v[32:35], v[80:81], v[76:77], v[32:35]
	s_nop 0
	v_mfma_f32_16x16x16_bf16 v[36:39], v[80:81], v[72:73], v[36:39]
	v_mov_b32_e32 v28, v82
	v_mov_b32_e32 v29, v83
	s_nop 1
	v_mfma_f32_16x16x16_bf16 v[80:83], v[28:29], v[0:1], v[40:43]
	s_nop 2
	v_mul_f32_e64 v42, v58, v26
	v_mul_f32_e64 v43, v59, v27
	v_pk_mul_f32 v[40:41], v[56:57], v[24:25]
	v_pk_mul_f32 v[26:27], v[62:63], v[26:27]
	v_pk_mul_f32 v[24:25], v[60:61], v[24:25]
	v_mfma_f32_16x16x16_bf16 v[76:79], v[28:29], v[76:77], v[40:43]
	s_nop 0
	v_mfma_f32_16x16x16_bf16 v[72:75], v[28:29], v[72:73], v[24:27]
	s_and_saveexec_b64 s[2:3], s[6:7]
	s_cbranch_execz .LBB0_615
	s_nop 0
	ds_read_b128 v[24:27], v203
	ds_read_b128 v[28:31], v160 offset:62976
	ds_read_b128 v[100:103], v203 offset:64
	ds_read_b128 v[104:107], v160 offset:63040
	ds_read_b128 v[40:43], v203 offset:128
	s_pack_ll_b32_b16 s20, 0, 0
	s_waitcnt lgkmcnt(3)
	v_mfma_f32_16x16x32_bf16 v[24:27], v[24:27], v[28:31], 0
	ds_read_b128 v[28:31], v160 offset:63104
	s_waitcnt lgkmcnt(2)
	v_mfma_f32_16x16x32_bf16 v[24:27], v[100:103], v[104:107], v[24:27]
	ds_read_b128 v[100:103], v203 offset:192
	ds_read_b128 v[104:107], v160 offset:63168
	s_waitcnt lgkmcnt(2)
	v_mfma_f32_16x16x32_bf16 v[24:27], v[40:43], v[28:31], v[24:27]
	s_waitcnt lgkmcnt(0)
	v_mfma_f32_16x16x32_bf16 v[24:27], v[100:103], v[104:107], v[24:27]
	s_nop 7
	v_cndmask_b32_e64 v0, v24, 0, s[8:9]
	v_cndmask_b32_e64 v1, 0, v25, s[10:11]
	v_cvt_pk_bf16_f32 v84, v0, v1
	v_cndmask_b32_e64 v0, v26, 0, s[12:13]
	v_cndmask_b32_e64 v1, v27, 0, s[14:15]
	v_cvt_pk_bf16_f32 v85, v0, v1
; template <int MODE>
; __device__ void scan_unit(int swave, const Params& p, int j, int b, int h, int dir, char* shm) {
;     ...
;     bf16x8 Bv[NVT];
; #pragma unroll
;     for (int t = 0; t < NVT; ++t) {
;       const uint2 vv = *(const uint2*)(vT + ((vt0 + t) * 16 + r) * VS + q4 * 4);
;       Bv[t] = (bf16x8){(short)(vv.x & 0xffff), (short)(vv.x >> 16), (short)(vv.y & 0xffff), (short)(vv.y >> 16), 0, 0, 0, 0};
;     }
;     bf16x8 Aq[2];
; #pragma unroll
;     for (int m = 0; m < 2; ++m) {
;       const uint2 lo = *(const uint2*)(qin + r * QS + slab + (2 * m) * 16 + q4 * 4);
;       const uint2 hi = *(const uint2*)(qin + r * QS + slab + (2 * m + 1) * 16 + q4 * 4);
;       Aq[m] = (bf16x8){(short)(lo.x & 0xffff), (short)(lo.x >> 16), (short)(lo.y & 0xffff), (short)(lo.y >> 16),
;                        (short)(hi.x & 0xffff), (short)(hi.x >> 16), (short)(hi.y & 0xffff), (short)(hi.y >> 16)};
;     }
;     f32x4 o[NVT];
; #pragma unroll
;     for (int t = 0; t < NVT; ++t) {
;       o[t] = (f32x4){0.f, 0.f, 0.f, 0.f};
;       if (KS == 1 || wk == 0) o[t] = __builtin_amdgcn_mfma_f32_16x16x32_bf16(Asc, Bv[t], o[t], 0, 0, 0);
;     }
.LBB0_615:
	s_or_b64 exec, exec, s[2:3]
	ds_read_b64 v[0:1], v204
	ds_read_b64 v[104:105], v205
	ds_read_b64 v[100:101], v206
	v_add_u32_e32 v24, 0xf000, v224
	ds_read2_b64 v[28:31], v24 offset0:192 offset1:196
	ds_read2_b64 v[24:27], v24 offset0:200 offset1:204
	v_mov_b32_e32 v2, v3
	v_mov_b32_e32 v40, 0
	v_mov_b32_e32 v44, 0
	v_mov_b32_e32 v45, 0
	v_mov_b32_e32 v46, 0
	v_mov_b32_e32 v47, 0
	s_and_saveexec_b64 s[2:3], s[6:7]
	s_cbranch_execz .LBB0_617
	s_waitcnt lgkmcnt(4)
	v_mfma_f32_16x16x16_bf16 v[44:47], v[84:85], v[0:1], 0
.LBB0_617:
	s_or_b64 exec, exec, s[2:3]
	v_mov_b32_e32 v106, v3
	v_mov_b32_e32 v107, v3
	v_mov_b32_e32 v41, 0
	v_mov_b32_e32 v42, 0
	v_mov_b32_e32 v43, 0
	s_and_saveexec_b64 s[2:3], s[6:7]
	s_cbranch_execz .LBB0_619
	s_waitcnt lgkmcnt(3)
	v_mfma_f32_16x16x16_bf16 v[40:43], v[84:85], v[104:105], 0
.LBB0_619:
	s_or_b64 exec, exec, s[2:3]
	v_mov_b32_e32 v102, v3
	v_mov_b32_e32 v103, v3
	v_mov_b32_e32 v48, 0
	v_mov_b32_e32 v49, 0
	v_mov_b32_e32 v50, 0
	v_mov_b32_e32 v51, 0
	s_and_saveexec_b64 s[2:3], s[6:7]
	s_cbranch_execz .LBB0_570
	s_waitcnt lgkmcnt(2)
	v_mfma_f32_16x16x16_bf16 v[48:51], v[84:85], v[100:101], 0
	s_branch .LBB0_570
